# code placement: the 4-byte pad moved in front of the up-projection unit loop (its K-loop head now at 0 mod 8 as well); same instructions as v67
# baseline (speedup 1.0000x reference)
.LBB0_100:
	s_load_dwordx2 s[20:21], s[66:67], 0x98
	s_waitcnt vmcnt(2)
	s_barrier
	v_and_b32_e32 v224, 63, v0
	v_mov_b32_e32 v147, v1
	s_waitcnt lgkmcnt(0)
	s_add_u32 s36, s20, 0x12500000
	s_addc_u32 s37, s21, 0
	s_add_u32 s18, s20, 0x10d00000
	s_addc_u32 s19, s21, 0
	s_lshl_b32 s6, s22, 1
	s_or_b32 s6, s6, 1
	s_ashr_i32 s7, s6, 31
	s_lshl_b64 s[6:7], s[6:7], 18
	s_add_u32 s38, s20, s6
	s_addc_u32 s39, s21, s7
	s_mul_i32 s7, s22, 0x10800
	s_mul_hi_i32 s6, s22, 0x10800
	s_add_u32 s44, s40, s7
	s_addc_u32 s45, s41, s6
	s_mul_i32 s7, s22, 0x5800
	s_mul_hi_i32 s6, s22, 0x5800
	s_add_u32 s48, s42, s7
	s_addc_u32 s49, s43, s6
	s_mov_b64 s[6:7], 0x80
	s_lshl_b32 s3, s3, 5
	s_add_i32 m0, s13, 0x18000
	v_lshl_add_u64 v[8:9], v[8:9], 0, s[6:7]
	s_and_b32 s21, s3, 0x60
	global_load_lds_dwordx4 v[8:9], off
	v_lshl_add_u64 v[6:7], v[6:7], 0, s[6:7]
	s_add_i32 m0, s13, 0x1a000
	s_add_i32 s22, s13, 0x8000
	s_lshl_b32 s20, s11, 6
	s_lshl_b32 s24, s11, 13
	s_lshl_b32 s3, s21, 7
	global_load_lds_dwordx4 v[6:7], off
	v_lshl_add_u64 v[2:3], v[2:3], 0, s[6:7]
	s_mov_b32 m0, s22
	s_add_i32 s23, s13, 0xa000
	global_load_lds_dwordx4 v[2:3], off
	v_lshl_add_u64 v[2:3], v[4:5], 0, s[6:7]
	s_add_u32 s6, s0, 0x40080
	s_mov_b32 m0, s23
	s_addc_u32 s7, s1, 0
	global_load_lds_dwordx4 v[2:3], off
	s_add_i32 m0, s13, 0x1c000
	v_lshl_add_u64 v[2:3], s[6:7], 0, v[140:141]
	global_load_lds_dwordx4 v[2:3], off
	v_lshl_add_u64 v[2:3], s[6:7], 0, v[144:145]
	s_add_i32 m0, s13, 0x1e000
	s_movk_i32 s6, 0x3c0
	global_load_lds_dwordx4 v[2:3], off
	v_and_b32_e32 v2, 48, v0
	v_lshlrev_b32_e32 v3, 6, v0
	v_and_or_b32 v2, v3, s6, v2
	v_lshlrev_b32_e32 v3, 2, v0
	v_and_b32_e32 v3, 32, v3
	s_cmpk_lt_u32 s2, 0x100
	v_bitop3_b32 v4, v2, s24, v3 bitop3:0xde
	s_cselect_b64 s[56:57], -1, 0
	s_ashr_i32 s24, s17, 31
	s_ashr_i32 s25, s8, 31
	s_add_u32 s60, s44, 0x5800
	s_addc_u32 s61, s45, 0
	s_add_u32 s2, s44, 0xb000
	v_bitop3_b32 v223, s3, v2, v3 bitop3:0xf6
	s_addc_u32 s3, s45, 0
	v_lshlrev_b32_e32 v0, 14, v10
	s_add_u32 s96, s44, 0x2c00
	v_and_b32_e32 v0, 0xffff8000, v0
	s_addc_u32 s97, s45, 0
	v_lshl_add_u32 v0, v11, 11, v0
	v_and_b32_e32 v2, 1, v10
	s_add_u32 s62, s44, 0x8400
	v_lshl_or_b32 v0, v2, 6, v0
	s_addc_u32 s63, s45, 0
	v_lshl_add_u32 v146, v12, 1, v0
	v_lshlrev_b32_e32 v0, 14, v13
	s_add_u32 s64, s44, 0xdc00
	v_and_b32_e32 v0, 0xffff8000, v0
	s_waitcnt vmcnt(6)
	s_addc_u32 s65, s45, 0
	v_lshl_add_u32 v0, v14, 11, v0
	v_and_b32_e32 v2, 1, v13
	s_add_u32 s66, s48, 0x2c00
	v_lshl_or_b32 v0, v2, 6, v0
	s_addc_u32 s67, s49, 0
	v_lshl_add_u32 v148, v15, 1, v0
	v_mov_b32_e32 v149, v1
	s_mov_b32 s26, 0
	v_add_u32_e32 v225, 0, v4
	s_barrier
	s_branch .LBB0_103
	s_nop 0
